# pass B (chunk start states) rewritten: LDS-DMA ring prefetch 6 steps ahead, one barrier per step, single-row S buffer
# speedup vs baseline: 1.0493x; 1.0196x over previous
.LBB0_589:
	s_andn2_b64 vcc, exec, s[2:3]
	s_cbranch_vccnz .LBB0_594
	s_ashr_i32 s2, s33, 3
	s_mul_hi_i32 s3, s2, 0x280000
	s_mul_i32 s2, s2, 0x280000
	s_add_u32 s4, s88, s2
	s_addc_u32 s5, s89, s3
	s_add_u32 s4, s4, 0x6180000
	s_addc_u32 s5, s5, 0
	v_readfirstlane_b32 s6, v188
	s_lshr_b32 s6, s6, 6
	v_lshlrev_b32_e32 v2, 4, v1
	s_lshl_b32 s7, s6, 11
	v_add_u32_e32 v2, s7, v2
	s_and_b32 s8, s33, 7
	s_lshl_b32 s8, s8, 3
	s_add_i32 s8, s8, s6
	s_lshl_b32 s8, s8, 8
	s_addk_i32 s8, 0x4000
	v_lshl_add_u32 v3, v1, 2, s8
	v_lshlrev_b32_e32 v4, 2, v1
	s_lshl_b32 s9, s6, 8
	v_add_u32_e32 v5, s9, v4
	v_mov_b32_e32 v6, s9
	v_mov_b32_e32 v7, 0
	ds_write_b32 v5, v7
	s_add_i32 s14, s7, 20480
	s_add_i32 s15, s9, 4096
	s_mov_b64 s[10:11], s[4:5]
	s_add_i32 m0, s14, 0
	s_nop 0
	global_load_lds_dwordx4 v2, s[10:11]
	global_load_lds_dwordx4 v2, s[10:11] offset:1024
	s_add_i32 m0, s15, 0
	s_nop 0
	global_load_lds_dword v3, s[10:11]
	global_load_dword v8, v3, s[10:11]
	s_add_u32 s10, s10, 0x8000
	s_addc_u32 s11, s11, 0
	s_add_i32 m0, s14, 16384
	s_nop 0
	global_load_lds_dwordx4 v2, s[10:11]
	global_load_lds_dwordx4 v2, s[10:11] offset:1024
	s_add_i32 m0, s15, 2048
	s_nop 0
	global_load_lds_dword v3, s[10:11]
	global_load_dword v8, v3, s[10:11]
	s_add_u32 s10, s10, 0x8000
	s_addc_u32 s11, s11, 0
	s_add_i32 m0, s14, 32768
	s_nop 0
	global_load_lds_dwordx4 v2, s[10:11]
	global_load_lds_dwordx4 v2, s[10:11] offset:1024
	s_add_i32 m0, s15, 4096
	s_nop 0
	global_load_lds_dword v3, s[10:11]
	global_load_dword v8, v3, s[10:11]
	s_add_u32 s10, s10, 0x8000
	s_addc_u32 s11, s11, 0
	s_add_i32 m0, s14, 49152
	s_nop 0
	global_load_lds_dwordx4 v2, s[10:11]
	global_load_lds_dwordx4 v2, s[10:11] offset:1024
	s_add_i32 m0, s15, 6144
	s_nop 0
	global_load_lds_dword v3, s[10:11]
	global_load_dword v8, v3, s[10:11]
	s_add_u32 s10, s10, 0x8000
	s_addc_u32 s11, s11, 0
	s_add_i32 m0, s14, 65536
	s_nop 0
	global_load_lds_dwordx4 v2, s[10:11]
	global_load_lds_dwordx4 v2, s[10:11] offset:1024
	s_add_i32 m0, s15, 8192
	s_nop 0
	global_load_lds_dword v3, s[10:11]
	global_load_dword v8, v3, s[10:11]
	s_add_u32 s10, s10, 0x8000
	s_addc_u32 s11, s11, 0
	s_add_i32 m0, s14, 81920
	s_nop 0
	global_load_lds_dwordx4 v2, s[10:11]
	global_load_lds_dwordx4 v2, s[10:11] offset:1024
	s_add_i32 m0, s15, 10240
	s_nop 0
	global_load_lds_dword v3, s[10:11]
	global_load_dword v8, v3, s[10:11]
	s_add_u32 s10, s10, 0x8000
	s_addc_u32 s11, s11, 0
	s_mov_b64 s[12:13], s[4:5]
	s_mov_b32 s16, 0
	s_mov_b32 s17, 0
	s_mov_b32 s18, 6
.Lpb_loop:
	s_waitcnt vmcnt(21)
	s_waitcnt lgkmcnt(0)
	s_barrier
	s_lshl_b32 s19, s18, 14
	s_add_i32 m0, s14, s19
	s_lshl_b32 s20, s17, 14
	global_load_lds_dwordx4 v2, s[10:11]
	global_load_lds_dwordx4 v2, s[10:11] offset:1024
	s_lshl_b32 s19, s18, 11
	s_add_i32 m0, s15, s19
	s_add_i32 s21, s20, 20480
	global_load_lds_dword v3, s[10:11]
	v_add_u32_e32 v9, s21, v4
	s_lshl_b32 s22, s17, 11
	s_add_i32 s22, s22, 4096
	v_add_u32_e32 v10, s22, v5
	ds_read_b32 v11, v10
	ds_read_b128 v[20:23], v6 offset:0
	ds_read_b128 v[24:27], v6 offset:16
	ds_read2st64_b32 v[36:37], v9 offset0:0 offset1:1
	ds_read2st64_b32 v[38:39], v9 offset0:2 offset1:3
	ds_read2st64_b32 v[40:41], v9 offset0:4 offset1:5
	ds_read2st64_b32 v[42:43], v9 offset0:6 offset1:7
	ds_read_b128 v[28:31], v6 offset:32
	ds_read_b128 v[32:35], v6 offset:48
	ds_read2st64_b32 v[44:45], v9 offset0:8 offset1:9
	ds_read2st64_b32 v[46:47], v9 offset0:10 offset1:11
	ds_read2st64_b32 v[48:49], v9 offset0:12 offset1:13
	ds_read2st64_b32 v[50:51], v9 offset0:14 offset1:15
	s_waitcnt lgkmcnt(6)
	v_mul_f32_e32 v12, v20, v36
	v_mul_f32_e32 v13, v21, v37
	v_mul_f32_e32 v14, v22, v38
	v_mul_f32_e32 v15, v23, v39
	v_fmac_f32_e32 v12, v24, v40
	v_fmac_f32_e32 v13, v25, v41
	v_fmac_f32_e32 v14, v26, v42
	v_fmac_f32_e32 v15, v27, v43
	ds_read_b128 v[20:23], v6 offset:64
	ds_read_b128 v[24:27], v6 offset:80
	ds_read2st64_b32 v[36:37], v9 offset0:16 offset1:17
	ds_read2st64_b32 v[38:39], v9 offset0:18 offset1:19
	ds_read2st64_b32 v[40:41], v9 offset0:20 offset1:21
	ds_read2st64_b32 v[42:43], v9 offset0:22 offset1:23
	s_waitcnt lgkmcnt(6)
	v_fmac_f32_e32 v12, v28, v44
	v_fmac_f32_e32 v13, v29, v45
	v_fmac_f32_e32 v14, v30, v46
	v_fmac_f32_e32 v15, v31, v47
	v_fmac_f32_e32 v12, v32, v48
	v_fmac_f32_e32 v13, v33, v49
	v_fmac_f32_e32 v14, v34, v50
	v_fmac_f32_e32 v15, v35, v51
	ds_read_b128 v[28:31], v6 offset:96
	ds_read_b128 v[32:35], v6 offset:112
	ds_read2st64_b32 v[44:45], v9 offset0:24 offset1:25
	ds_read2st64_b32 v[46:47], v9 offset0:26 offset1:27
	ds_read2st64_b32 v[48:49], v9 offset0:28 offset1:29
	ds_read2st64_b32 v[50:51], v9 offset0:30 offset1:31
	s_waitcnt lgkmcnt(6)
	v_fmac_f32_e32 v12, v20, v36
	v_fmac_f32_e32 v13, v21, v37
	v_fmac_f32_e32 v14, v22, v38
	v_fmac_f32_e32 v15, v23, v39
	v_fmac_f32_e32 v12, v24, v40
	v_fmac_f32_e32 v13, v25, v41
	v_fmac_f32_e32 v14, v26, v42
	v_fmac_f32_e32 v15, v27, v43
	ds_read_b128 v[20:23], v6 offset:128
	ds_read_b128 v[24:27], v6 offset:144
	ds_read2st64_b32 v[36:37], v9 offset0:32 offset1:33
	ds_read2st64_b32 v[38:39], v9 offset0:34 offset1:35
	ds_read2st64_b32 v[40:41], v9 offset0:36 offset1:37
	ds_read2st64_b32 v[42:43], v9 offset0:38 offset1:39
	s_waitcnt lgkmcnt(6)
	v_fmac_f32_e32 v12, v28, v44
	v_fmac_f32_e32 v13, v29, v45
	v_fmac_f32_e32 v14, v30, v46
	v_fmac_f32_e32 v15, v31, v47
	v_fmac_f32_e32 v12, v32, v48
	v_fmac_f32_e32 v13, v33, v49
	v_fmac_f32_e32 v14, v34, v50
	v_fmac_f32_e32 v15, v35, v51
	ds_read_b128 v[28:31], v6 offset:160
	ds_read_b128 v[32:35], v6 offset:176
	ds_read2st64_b32 v[44:45], v9 offset0:40 offset1:41
	ds_read2st64_b32 v[46:47], v9 offset0:42 offset1:43
	ds_read2st64_b32 v[48:49], v9 offset0:44 offset1:45
	ds_read2st64_b32 v[50:51], v9 offset0:46 offset1:47
	s_waitcnt lgkmcnt(6)
	v_fmac_f32_e32 v12, v20, v36
	v_fmac_f32_e32 v13, v21, v37
	v_fmac_f32_e32 v14, v22, v38
	v_fmac_f32_e32 v15, v23, v39
	v_fmac_f32_e32 v12, v24, v40
	v_fmac_f32_e32 v13, v25, v41
	v_fmac_f32_e32 v14, v26, v42
	v_fmac_f32_e32 v15, v27, v43
	ds_read_b128 v[20:23], v6 offset:192
	ds_read_b128 v[24:27], v6 offset:208
	ds_read2st64_b32 v[36:37], v9 offset0:48 offset1:49
	ds_read2st64_b32 v[38:39], v9 offset0:50 offset1:51
	ds_read2st64_b32 v[40:41], v9 offset0:52 offset1:53
	ds_read2st64_b32 v[42:43], v9 offset0:54 offset1:55
	s_waitcnt lgkmcnt(6)
	v_fmac_f32_e32 v12, v28, v44
	v_fmac_f32_e32 v13, v29, v45
	v_fmac_f32_e32 v14, v30, v46
	v_fmac_f32_e32 v15, v31, v47
	v_fmac_f32_e32 v12, v32, v48
	v_fmac_f32_e32 v13, v33, v49
	v_fmac_f32_e32 v14, v34, v50
	v_fmac_f32_e32 v15, v35, v51
	ds_read_b128 v[28:31], v6 offset:224
	ds_read_b128 v[32:35], v6 offset:240
	ds_read2st64_b32 v[44:45], v9 offset0:56 offset1:57
	ds_read2st64_b32 v[46:47], v9 offset0:58 offset1:59
	ds_read2st64_b32 v[48:49], v9 offset0:60 offset1:61
	ds_read2st64_b32 v[50:51], v9 offset0:62 offset1:63
	s_waitcnt lgkmcnt(6)
	v_fmac_f32_e32 v12, v20, v36
	v_fmac_f32_e32 v13, v21, v37
	v_fmac_f32_e32 v14, v22, v38
	v_fmac_f32_e32 v15, v23, v39
	v_fmac_f32_e32 v12, v24, v40
	v_fmac_f32_e32 v13, v25, v41
	v_fmac_f32_e32 v14, v26, v42
	v_fmac_f32_e32 v15, v27, v43
	s_waitcnt lgkmcnt(0)
	v_fmac_f32_e32 v12, v28, v44
	v_fmac_f32_e32 v13, v29, v45
	v_fmac_f32_e32 v14, v30, v46
	v_fmac_f32_e32 v15, v31, v47
	v_fmac_f32_e32 v12, v32, v48
	v_fmac_f32_e32 v13, v33, v49
	v_fmac_f32_e32 v14, v34, v50
	v_fmac_f32_e32 v15, v35, v51
	v_add_f32_e32 v12, v12, v13
	v_add_f32_e32 v14, v14, v15
	v_add_f32_e32 v12, v12, v11
	v_add_f32_e32 v12, v12, v14
	ds_write_b32 v5, v12
	global_store_dword v3, v12, s[12:13]
	s_add_u32 s12, s12, 0x8000
	s_addc_u32 s13, s13, 0
	s_add_i32 s16, s16, 1
	s_cmp_lt_u32 s16, 73
	s_cselect_b32 s19, 0x8000, 0
	s_add_u32 s10, s10, s19
	s_addc_u32 s11, s11, 0
	s_add_i32 s17, s17, 1
	s_cmp_eq_u32 s17, 7
	s_cselect_b32 s17, 0, s17
	s_add_i32 s18, s18, 1
	s_cmp_eq_u32 s18, 7
	s_cselect_b32 s18, 0, s18
	s_cmp_eq_u32 s16, 79
	s_cbranch_scc0 .Lpb_loop
	s_waitcnt vmcnt(0) lgkmcnt(0)
	s_branch .LBB0_594
